# gemm_tile<4> K-loops (E1/O1): the 7 LDS read-address ALU ops moved ahead of the stage wait + barrier (off the barrier-to-first-ds_read path)
# baseline (speedup 1.0000x reference)
; DI int get_bid() { int b = blockIdx.x; asm volatile("" : "+s"(b)); return b; }
; template <int MT, class Epi>
; DI void gemm_tile(const u16* __restrict__ X, long ldx, const u16* __restrict__ W, long ldw, int K, char* smem,
;                   int m0, int n0, const Epi& epi, bool pre = false, const u16* Xn = nullptr, const u16* Wn = nullptr) {
;     ...
;   do {
;     asm volatile("s_waitcnt vmcnt(0)" ::: "memory");
;     __syncthreads();
;     if (kt + 1 < nk) GT_DMA((unsigned)((kt + 1) & 1) * 32768u)
;     else if (Xn != nullptr) { xe = Xn + oxe; xo = Xn + oxo; we = Wn + owe; wo = Wn + owo; GT_DMA(0u) }
;     const char* cur = smem + (kt & 1) * 32768;
; #pragma unroll
;     for (int ks = 0; ks < 2; ++ks) {
;       bf16x8 xf[MT], wf[4];
;       const int ch = ((ks * 4 + g) ^ rsw) << 4;
; #pragma unroll
;       for (int i = 0; i < MT; ++i) xf[i] = *(const bf16x8*)(cur + (wm * 16 * MT + i * 16 + lr) * 128 + ch);
; #pragma unroll
;       for (int i = 0; i < 4; ++i) wf[i] = *(const bf16x8*)(cur + 16384 + (wn * 64 + i * 16 + lr) * 128 + ch);
; #pragma unroll
;       for (int nt = 0; nt < 4; ++nt)
; #pragma unroll
;         for (int mt = 0; mt < MT; ++mt)
;           acc[nt][mt] = __builtin_amdgcn_mfma_f32_16x16x32_bf16(wf[nt], xf[mt], acc[nt][mt], 0, 0, 0);
;     }
;   } while (++kt < nk);
; DI void phase_odd(const Params& p, int o, int sub, char* smem) {
;     ...
;     for (int t = get_bid(); t < 132 * 14; t += gridDim.x) {
;       const int tm = t / 14, tn = t % 14;
;       const int t2 = t + gridDim.x, tm2 = t2 / 14, tn2 = t2 % 14;
;       const bool nx = t2 < 132 * 14;
;       gemm_tile<4>(hbuf + (size_t)tm * 128 * 1024, 1024, W + WO_IN + (size_t)tn * 128 * 1024, 1024, 1024, smem, tm * 128, tn * 128, epi, pre,
;                    nx ? hbuf + (size_t)tm2 * 128 * 1024 : nullptr, W + WO_IN + (size_t)tn2 * 128 * 1024);
;       pre = nx;
.LBB0_144:
	s_add_i32 s7, s8, 0x8000
	v_lshl_add_u64 v[124:125], v[76:77], 0, s[40:41]
	s_and_b32 s9, s7, 0x8000
	v_lshl_add_u64 v[122:123], v[74:75], 0, s[40:41]
	v_lshl_add_u64 v[126:127], v[124:125], 0, s[74:75]
	s_and_b32 s8, s8, 0x8000
	v_or_b32_e32 v162, s8, v85
	v_add3_u32 v163, v162, v81, v82
	v_add3_u32 v164, v162, v84, v82
	v_or_b32_e32 v165, s8, v83
	v_add3_u32 v166, v165, v81, v82
	v_add3_u32 v167, v165, v84, v82
	s_waitcnt vmcnt(0)
	s_barrier
	ds_read_b128 v[86:89], v163
	ds_read_b128 v[90:93], v163 offset:2048
	ds_read_b128 v[94:97], v163 offset:4096
	ds_read_b128 v[98:101], v163 offset:6144
	ds_read_b128 v[102:105], v164 offset:16384
	ds_read_b128 v[106:109], v164 offset:18432
	ds_read_b128 v[110:113], v164 offset:20480
	ds_read_b128 v[114:117], v164 offset:22528
	ds_read_b128 v[130:133], v166
	ds_read_b128 v[134:137], v166 offset:2048
	ds_read_b128 v[138:141], v166 offset:4096
	ds_read_b128 v[142:145], v166 offset:6144
	ds_read_b128 v[146:149], v167 offset:16384
	ds_read_b128 v[150:153], v167 offset:18432
	ds_read_b128 v[154:157], v167 offset:20480
	ds_read_b128 v[158:161], v167 offset:22528
	s_add_i32 s10, s9, s5
	s_mov_b32 m0, s10
	s_nop 0
	global_load_lds_dwordx4 v[126:127], off
	v_lshl_add_u64 v[126:127], v[122:123], 0, s[94:95]
	s_add_i32 s11, s10, 0x400
	s_mov_b32 m0, s11
	s_nop 0
	global_load_lds_dwordx4 v[126:127], off
	v_lshl_add_u64 v[124:125], v[124:125], 0, s[76:77]
	s_add_i32 s11, s10, 0x800
	s_mov_b32 m0, s11
	s_nop 0
	global_load_lds_dwordx4 v[124:125], off
	v_lshl_add_u64 v[120:121], v[72:73], 0, s[40:41]
	v_lshl_add_u64 v[122:123], v[122:123], 0, s[54:55]
	s_addk_i32 s10, 0xc00
	s_mov_b32 m0, s10
	s_nop 0
	global_load_lds_dwordx4 v[122:123], off
	v_lshl_add_u64 v[118:119], v[70:71], 0, s[40:41]
	v_lshl_add_u64 v[128:129], v[120:121], 0, s[28:29]
	s_add_i32 s9, s9, s6
	s_mov_b32 m0, s9
	s_nop 0
	global_load_lds_dwordx4 v[128:129], off
	v_lshl_add_u64 v[122:123], v[118:119], 0, s[94:95]
	s_add_i32 s10, s9, 0x400
	s_mov_b32 m0, s10
	s_nop 0
	global_load_lds_dwordx4 v[122:123], off
	v_lshl_add_u64 v[120:121], v[120:121], 0, s[78:79]
	s_add_i32 s10, s9, 0x800
	s_mov_b32 m0, s10
	s_nop 0
	global_load_lds_dwordx4 v[120:121], off
	v_lshl_add_u64 v[118:119], v[118:119], 0, s[54:55]
	s_addk_i32 s9, 0xc00
	s_mov_b32 m0, s9
	s_nop 0
	global_load_lds_dwordx4 v[118:119], off
	s_mov_b32 s8, s7
	s_add_u32 s40, s40, 0x80
	s_addc_u32 s41, s41, 0
	s_cmpk_lg_i32 s40, 0x780
	s_waitcnt lgkmcnt(11)
	v_mfma_f32_16x16x32_bf16 v[62:65], v[102:105], v[86:89], v[62:65]
	v_mfma_f32_16x16x32_bf16 v[58:61], v[102:105], v[90:93], v[58:61]
	v_mfma_f32_16x16x32_bf16 v[54:57], v[102:105], v[94:97], v[54:57]
	v_mfma_f32_16x16x32_bf16 v[50:53], v[102:105], v[98:101], v[50:53]
	s_waitcnt lgkmcnt(10)
	v_mfma_f32_16x16x32_bf16 v[34:37], v[106:109], v[98:101], v[34:37]
	s_waitcnt lgkmcnt(9)
	v_mfma_f32_16x16x32_bf16 v[18:21], v[110:113], v[98:101], v[18:21]
	s_waitcnt lgkmcnt(8)
	v_mfma_f32_16x16x32_bf16 v[14:17], v[114:117], v[86:89], v[14:17]
	v_mfma_f32_16x16x32_bf16 v[10:13], v[114:117], v[90:93], v[10:13]
	v_mfma_f32_16x16x32_bf16 v[6:9], v[114:117], v[94:97], v[6:9]
	v_mfma_f32_16x16x32_bf16 v[2:5], v[114:117], v[98:101], v[2:5]
	v_mfma_f32_16x16x32_bf16 v[46:49], v[106:109], v[86:89], v[46:49]
	v_mfma_f32_16x16x32_bf16 v[42:45], v[106:109], v[90:93], v[42:45]
	v_mfma_f32_16x16x32_bf16 v[38:41], v[106:109], v[94:97], v[38:41]
	v_mfma_f32_16x16x32_bf16 v[30:33], v[110:113], v[86:89], v[30:33]
	v_mfma_f32_16x16x32_bf16 v[26:29], v[110:113], v[90:93], v[26:29]
	v_mfma_f32_16x16x32_bf16 v[22:25], v[110:113], v[94:97], v[22:25]
	s_waitcnt lgkmcnt(3)
	v_mfma_f32_16x16x32_bf16 v[62:65], v[146:149], v[130:133], v[62:65]
	v_mfma_f32_16x16x32_bf16 v[58:61], v[146:149], v[134:137], v[58:61]
	v_mfma_f32_16x16x32_bf16 v[54:57], v[146:149], v[138:141], v[54:57]
	v_mfma_f32_16x16x32_bf16 v[50:53], v[146:149], v[142:145], v[50:53]
	s_waitcnt lgkmcnt(2)
	v_mfma_f32_16x16x32_bf16 v[46:49], v[150:153], v[130:133], v[46:49]
	v_mfma_f32_16x16x32_bf16 v[42:45], v[150:153], v[134:137], v[42:45]
	v_mfma_f32_16x16x32_bf16 v[38:41], v[150:153], v[138:141], v[38:41]
	v_mfma_f32_16x16x32_bf16 v[34:37], v[150:153], v[142:145], v[34:37]
	s_waitcnt lgkmcnt(1)
	v_mfma_f32_16x16x32_bf16 v[30:33], v[154:157], v[130:133], v[30:33]
	v_mfma_f32_16x16x32_bf16 v[26:29], v[154:157], v[134:137], v[26:29]
	v_mfma_f32_16x16x32_bf16 v[22:25], v[154:157], v[138:141], v[22:25]
	v_mfma_f32_16x16x32_bf16 v[18:21], v[154:157], v[142:145], v[18:21]
	s_waitcnt lgkmcnt(0)
	v_mfma_f32_16x16x32_bf16 v[14:17], v[158:161], v[130:133], v[14:17]
	v_mfma_f32_16x16x32_bf16 v[10:13], v[158:161], v[134:137], v[10:13]
	v_mfma_f32_16x16x32_bf16 v[6:9], v[158:161], v[138:141], v[6:9]
	v_mfma_f32_16x16x32_bf16 v[2:5], v[158:161], v[142:145], v[2:5]
	s_cbranch_scc1 .LBB0_144
	v_readlane_b32 s8, v255, 5
	v_readlane_b32 s14, v255, 11
	s_add_i32 s4, s4, s14
	s_mul_hi_i32 s7, s4, 0x92492493
	s_add_i32 s7, s7, s4
	s_lshr_b32 s8, s7, 31
	s_ashr_i32 s7, s7, 3
	s_add_i32 s46, s7, s8
	s_cmpk_gt_i32 s4, 0x737
	v_readlane_b32 s9, v255, 6
	s_cselect_b64 s[40:41], -1, 0
	s_ashr_i32 s47, s46, 31
	s_lshl_b64 s[8:9], s[46:47], 18
	s_add_u32 s7, s0, s8
	s_addc_u32 s8, s1, s9
	s_cmpk_lt_i32 s4, 0x738
	s_waitcnt vmcnt(0)
	s_cselect_b32 s45, s8, 0
	s_cselect_b32 s44, s7, 0
	v_readlane_b32 s12, v255, 9
	v_readlane_b32 s13, v255, 10
	s_cmp_eq_u64 s[44:45], 0
	v_readlane_b32 s10, v255, 7
	v_readlane_b32 s11, v255, 8
	v_readlane_b32 s15, v255, 12
	s_barrier
	s_cbranch_scc1 .LBB0_147
	s_mul_i32 s7, s46, 14
	s_sub_i32 s8, s4, s7
	s_ashr_i32 s9, s8, 31
	s_lshl_b64 s[8:9], s[8:9], 18
	s_add_u32 s8, s12, s8
	s_addc_u32 s9, s13, s9
	v_lshl_add_u64 v[70:71], s[44:45], 0, v[68:69]
	v_lshl_add_u64 v[72:73], s[8:9], 0, v[66:67]
	v_lshl_add_u64 v[66:67], s[44:45], 0, v[66:67]
	s_mov_b32 m0, s5
	s_nop 0
	global_load_lds_dwordx4 v[70:71], off
	s_mov_b64 s[10:11], 0x4000
	v_lshl_add_u64 v[68:69], s[8:9], 0, v[68:69]
	v_lshl_add_u64 v[74:75], v[66:67], 0, s[10:11]
	s_add_i32 s7, s5, 0x400
	s_mov_b32 m0, s7
	s_nop 0
	global_load_lds_dwordx4 v[74:75], off
	s_mov_b64 s[12:13], 0x8000
	v_lshl_add_u64 v[70:71], v[70:71], 0, s[12:13]
	s_add_i32 s7, s5, 0x800
	s_mov_b32 m0, s7
	s_nop 0
	global_load_lds_dwordx4 v[70:71], off
	s_mov_b64 s[14:15], 0xc000
	v_lshl_add_u64 v[66:67], v[66:67], 0, s[14:15]
	s_add_i32 s7, s5, 0xc00
	s_mov_b32 m0, s7
	s_nop 0
	global_load_lds_dwordx4 v[66:67], off
	s_mov_b32 m0, s6
	s_nop 0
	global_load_lds_dwordx4 v[68:69], off
	v_lshl_add_u64 v[66:67], v[72:73], 0, s[10:11]
	s_add_i32 s6, s5, 0x4400
	s_mov_b32 m0, s6
	s_nop 0
	global_load_lds_dwordx4 v[66:67], off
	v_lshl_add_u64 v[66:67], v[68:69], 0, s[12:13]
	s_add_i32 s6, s5, 0x4800
	s_mov_b32 m0, s6
	s_nop 0
	global_load_lds_dwordx4 v[66:67], off
	v_lshl_add_u64 v[66:67], v[72:73], 0, s[14:15]
	s_addk_i32 s5, 0x4c00
	s_mov_b32 m0, s5
	s_nop 0
	global_load_lds_dwordx4 v[66:67], off

; template <int MT, class Epi>
; DI void gemm_tile(const u16* __restrict__ X, long ldx, const u16* __restrict__ W, long ldw, int K, char* smem,
;                   int m0, int n0, const Epi& epi, bool pre = false, const u16* Xn = nullptr, const u16* Wn = nullptr) {
;     ...
;   do {
;     asm volatile("s_waitcnt vmcnt(0)" ::: "memory");
;     __syncthreads();
;     if (kt + 1 < nk) GT_DMA((unsigned)((kt + 1) & 1) * 32768u)
;     else if (Xn != nullptr) { xe = Xn + oxe; xo = Xn + oxo; we = Wn + owe; wo = Wn + owo; GT_DMA(0u) }
;     const char* cur = smem + (kt & 1) * 32768;
; #pragma unroll
;     for (int ks = 0; ks < 2; ++ks) {
;       bf16x8 xf[MT], wf[4];
;       const int ch = ((ks * 4 + g) ^ rsw) << 4;
; #pragma unroll
;       for (int i = 0; i < MT; ++i) xf[i] = *(const bf16x8*)(cur + (wm * 16 * MT + i * 16 + lr) * 128 + ch);
; #pragma unroll
;       for (int i = 0; i < 4; ++i) wf[i] = *(const bf16x8*)(cur + 16384 + (wn * 64 + i * 16 + lr) * 128 + ch);
; #pragma unroll
;       for (int nt = 0; nt < 4; ++nt)
; #pragma unroll
;         for (int mt = 0; mt < MT; ++mt)
;           acc[nt][mt] = __builtin_amdgcn_mfma_f32_16x16x32_bf16(wf[nt], xf[mt], acc[nt][mt], 0, 0, 0);
;     }
;   } while (++kt < nk);
.LBB0_422:
	s_add_i32 s7, s8, 0x8000
	v_lshl_add_u64 v[124:125], v[76:77], 0, s[40:41]
	s_and_b32 s9, s7, 0x8000
	v_lshl_add_u64 v[122:123], v[74:75], 0, s[40:41]
	v_lshl_add_u64 v[126:127], v[124:125], 0, s[74:75]
	s_and_b32 s8, s8, 0x8000
	v_or_b32_e32 v162, s8, v85
	v_add3_u32 v163, v162, v81, v82
	v_add3_u32 v164, v162, v84, v82
	v_or_b32_e32 v165, s8, v83
	v_add3_u32 v166, v165, v81, v82
	v_add3_u32 v167, v165, v84, v82
	s_waitcnt vmcnt(0)
	s_barrier
	ds_read_b128 v[86:89], v163
	ds_read_b128 v[90:93], v163 offset:2048
	ds_read_b128 v[94:97], v163 offset:4096
	ds_read_b128 v[98:101], v163 offset:6144
	ds_read_b128 v[102:105], v164 offset:16384
	ds_read_b128 v[106:109], v164 offset:18432
	ds_read_b128 v[110:113], v164 offset:20480
	ds_read_b128 v[114:117], v164 offset:22528
	ds_read_b128 v[130:133], v166
	ds_read_b128 v[134:137], v166 offset:2048
	ds_read_b128 v[138:141], v166 offset:4096
	ds_read_b128 v[142:145], v166 offset:6144
	ds_read_b128 v[146:149], v167 offset:16384
	ds_read_b128 v[150:153], v167 offset:18432
	ds_read_b128 v[154:157], v167 offset:20480
	ds_read_b128 v[158:161], v167 offset:22528
	s_add_i32 s10, s9, s5
	s_mov_b32 m0, s10
	s_nop 0
	global_load_lds_dwordx4 v[126:127], off
	v_lshl_add_u64 v[126:127], v[122:123], 0, s[94:95]
	s_add_i32 s11, s10, 0x400
	s_mov_b32 m0, s11
	s_nop 0
	global_load_lds_dwordx4 v[126:127], off
	v_lshl_add_u64 v[124:125], v[124:125], 0, s[76:77]
	s_add_i32 s11, s10, 0x800
	s_mov_b32 m0, s11
	s_nop 0
	global_load_lds_dwordx4 v[124:125], off
	v_lshl_add_u64 v[120:121], v[72:73], 0, s[40:41]
	v_lshl_add_u64 v[122:123], v[122:123], 0, s[54:55]
	s_addk_i32 s10, 0xc00
	s_mov_b32 m0, s10
	s_nop 0
	global_load_lds_dwordx4 v[122:123], off
	v_lshl_add_u64 v[118:119], v[70:71], 0, s[40:41]
	v_lshl_add_u64 v[128:129], v[120:121], 0, s[28:29]
	s_add_i32 s9, s9, s6
	s_mov_b32 m0, s9
	s_nop 0
	global_load_lds_dwordx4 v[128:129], off
	v_lshl_add_u64 v[122:123], v[118:119], 0, s[94:95]
	s_add_i32 s10, s9, 0x400
	s_mov_b32 m0, s10
	s_nop 0
	global_load_lds_dwordx4 v[122:123], off
	v_lshl_add_u64 v[120:121], v[120:121], 0, s[78:79]
	s_add_i32 s10, s9, 0x800
	s_mov_b32 m0, s10
	s_nop 0
	global_load_lds_dwordx4 v[120:121], off
	v_lshl_add_u64 v[118:119], v[118:119], 0, s[54:55]
	s_addk_i32 s9, 0xc00
	s_mov_b32 m0, s9
	s_nop 0
	global_load_lds_dwordx4 v[118:119], off
	s_mov_b32 s8, s7
	s_add_u32 s40, s40, 0x80
	s_addc_u32 s41, s41, 0
	s_cmpk_lg_i32 s40, 0x780
	s_waitcnt lgkmcnt(11)
	v_mfma_f32_16x16x32_bf16 v[62:65], v[102:105], v[86:89], v[62:65]
	v_mfma_f32_16x16x32_bf16 v[58:61], v[102:105], v[90:93], v[58:61]
	v_mfma_f32_16x16x32_bf16 v[54:57], v[102:105], v[94:97], v[54:57]
	v_mfma_f32_16x16x32_bf16 v[50:53], v[102:105], v[98:101], v[50:53]
	s_waitcnt lgkmcnt(10)
	v_mfma_f32_16x16x32_bf16 v[34:37], v[106:109], v[98:101], v[34:37]
	s_waitcnt lgkmcnt(9)
	v_mfma_f32_16x16x32_bf16 v[18:21], v[110:113], v[98:101], v[18:21]
	s_waitcnt lgkmcnt(8)
	v_mfma_f32_16x16x32_bf16 v[14:17], v[114:117], v[86:89], v[14:17]
	v_mfma_f32_16x16x32_bf16 v[10:13], v[114:117], v[90:93], v[10:13]
	v_mfma_f32_16x16x32_bf16 v[6:9], v[114:117], v[94:97], v[6:9]
	v_mfma_f32_16x16x32_bf16 v[2:5], v[114:117], v[98:101], v[2:5]
	v_mfma_f32_16x16x32_bf16 v[46:49], v[106:109], v[86:89], v[46:49]
	v_mfma_f32_16x16x32_bf16 v[42:45], v[106:109], v[90:93], v[42:45]
	v_mfma_f32_16x16x32_bf16 v[38:41], v[106:109], v[94:97], v[38:41]
	v_mfma_f32_16x16x32_bf16 v[30:33], v[110:113], v[86:89], v[30:33]
	v_mfma_f32_16x16x32_bf16 v[26:29], v[110:113], v[90:93], v[26:29]
	v_mfma_f32_16x16x32_bf16 v[22:25], v[110:113], v[94:97], v[22:25]
	s_waitcnt lgkmcnt(3)
	v_mfma_f32_16x16x32_bf16 v[62:65], v[146:149], v[130:133], v[62:65]
	v_mfma_f32_16x16x32_bf16 v[58:61], v[146:149], v[134:137], v[58:61]
	v_mfma_f32_16x16x32_bf16 v[54:57], v[146:149], v[138:141], v[54:57]
	v_mfma_f32_16x16x32_bf16 v[50:53], v[146:149], v[142:145], v[50:53]
	s_waitcnt lgkmcnt(2)
	v_mfma_f32_16x16x32_bf16 v[46:49], v[150:153], v[130:133], v[46:49]
	v_mfma_f32_16x16x32_bf16 v[42:45], v[150:153], v[134:137], v[42:45]
	v_mfma_f32_16x16x32_bf16 v[38:41], v[150:153], v[138:141], v[38:41]
	v_mfma_f32_16x16x32_bf16 v[34:37], v[150:153], v[142:145], v[34:37]
	s_waitcnt lgkmcnt(1)
	v_mfma_f32_16x16x32_bf16 v[30:33], v[154:157], v[130:133], v[30:33]
	v_mfma_f32_16x16x32_bf16 v[26:29], v[154:157], v[134:137], v[26:29]
	v_mfma_f32_16x16x32_bf16 v[22:25], v[154:157], v[138:141], v[22:25]
	v_mfma_f32_16x16x32_bf16 v[18:21], v[154:157], v[142:145], v[18:21]
	s_waitcnt lgkmcnt(0)
	v_mfma_f32_16x16x32_bf16 v[14:17], v[158:161], v[130:133], v[14:17]
	v_mfma_f32_16x16x32_bf16 v[10:13], v[158:161], v[134:137], v[10:13]
	v_mfma_f32_16x16x32_bf16 v[6:9], v[158:161], v[138:141], v[6:9]
	v_mfma_f32_16x16x32_bf16 v[2:5], v[158:161], v[142:145], v[2:5]
	s_cbranch_scc1 .LBB0_422
; DI int get_bid() { int b = blockIdx.x; asm volatile("" : "+s"(b)); return b; }
; DI float gelu_f(float x) { return 0.5f * x * (1.f + erff(x * 0.70710678118654752f)); }
; DI float silu_f(float x) { return x * __builtin_amdgcn_rcpf(1.f + __expf(-x)); }
; DI void phase_even(const Params& p, int e, int sub, char* smem) {
;     ...
;     for (int t = get_bid(); t < 132 * 40; t += gridDim.x) {
;       const int tm = t / 40, tn = t % 40;
;       const int t2 = t + gridDim.x, tm2 = t2 / 40, tn2 = t2 % 40;
;       const bool nx = t2 < 132 * 40;
;       gemm_tile<4>(hbuf + (size_t)tm * 128 * 1024, 1024, W + WE_IN + (size_t)tn * 128 * 1024, 1024, 1024, smem, tm * 128, tn * 128, epi, pre,
;                    nx ? hbuf + (size_t)tm2 * 128 * 1024 : nullptr, W + WE_IN + (size_t)tn2 * 128 * 1024);
;       pre = nx;
;     }
	v_mov_b32_e32 v170, 0x3f3504f3
	v_mov_b32_e32 v171, 0x3f3504f3
	v_mov_b32_e32 v172, 0xbfb8aa3b
	v_mov_b32_e32 v173, 0xbfb8aa3b
	v_mov_b32_e32 v174, 0x378e98ab
	v_mov_b32_e32 v175, 0x378e98ab
	v_mov_b32_e32 v176, 0xb9c68948
	v_mov_b32_e32 v177, 0xb9c68948
	v_mov_b32_e32 v178, 0x3b7cd369
	v_mov_b32_e32 v179, 0x3b7cd369
	v_mov_b32_e32 v180, 0xbcc618b2
	v_mov_b32_e32 v181, 0xbcc618b2
	v_mov_b32_e32 v186, 0x3dda74e4
	v_mov_b32_e32 v187, 0x3dda74e4
	v_mov_b32_e32 v188, 0x3f228afd
	v_mov_b32_e32 v189, 0x3f228afd
	v_mov_b32_e32 v190, 0x3e03c728
	v_mov_b32_e32 v191, 0x3e03c728
	v_mov_b32_e32 v192, 0xba1345e1
	v_mov_b32_e32 v193, 0xba1345e1
	v_mov_b32_e32 v194, 0x3ba10414
	v_mov_b32_e32 v195, 0x3ba10414
	v_mov_b32_e32 v196, 0xbcdac9b8
	v_mov_b32_e32 v197, 0xbcdac9b8
	v_mov_b32_e32 v224, 0x3de703be
	v_mov_b32_e32 v225, 0x3de703be
	v_mov_b32_e32 v226, 0xbec09330
	v_mov_b32_e32 v227, 0xbec09330
	v_mov_b32_e32 v228, 0x3e0375d0
	v_mov_b32_e32 v229, 0x3e0375d0
	v_mov_b32_e32 v230, 1.0
	v_mov_b32_e32 v231, 1.0
	v_mov_b32_e32 v232, 0.5
	v_mov_b32_e32 v233, 0.5
	v_mov_b32_e32 v234, -1.0
	v_mov_b32_e32 v235, -1.0
	v_readlane_b32 s8, v255, 5
	v_readlane_b32 s14, v255, 11
	s_add_i32 s4, s4, s14
	s_mul_hi_i32 s7, s4, 0x66666667
	s_lshr_b32 s8, s7, 31
	s_ashr_i32 s7, s7, 4
	s_add_i32 s46, s7, s8
	s_cmpk_gt_i32 s4, 0x149f
	v_readlane_b32 s9, v255, 6
	s_cselect_b64 s[44:45], -1, 0
	s_ashr_i32 s47, s46, 31
	s_lshl_b64 s[8:9], s[46:47], 18
	s_add_u32 s7, s0, s8
	s_addc_u32 s8, s1, s9
	s_cmpk_lt_i32 s4, 0x14a0
	s_waitcnt vmcnt(0)
	s_cselect_b32 s41, s8, 0
	s_cselect_b32 s40, s7, 0
	v_readlane_b32 s12, v255, 9
	v_readlane_b32 s13, v255, 10
	s_cmp_eq_u64 s[40:41], 0
	v_readlane_b32 s10, v255, 7
	v_readlane_b32 s11, v255, 8
	v_readlane_b32 s15, v255, 12
	s_barrier
	s_cbranch_scc1 .LBB0_425
	s_mul_i32 s7, s46, 40
	s_sub_i32 s8, s4, s7
	s_ashr_i32 s9, s8, 31
	s_lshl_b64 s[8:9], s[8:9], 18
	s_add_u32 s8, s12, s8
	s_addc_u32 s9, s13, s9
	v_lshl_add_u64 v[70:71], s[40:41], 0, v[68:69]
	v_lshl_add_u64 v[72:73], s[8:9], 0, v[66:67]
	v_lshl_add_u64 v[66:67], s[40:41], 0, v[66:67]
	s_mov_b32 m0, s5
	s_nop 0
	global_load_lds_dwordx4 v[70:71], off
	s_mov_b64 s[10:11], 0x4000
	v_lshl_add_u64 v[68:69], s[8:9], 0, v[68:69]
	v_lshl_add_u64 v[74:75], v[66:67], 0, s[10:11]
	s_add_i32 s7, s5, 0x400
	s_mov_b32 m0, s7
	s_nop 0
	global_load_lds_dwordx4 v[74:75], off
	s_mov_b64 s[12:13], 0x8000
	v_lshl_add_u64 v[70:71], v[70:71], 0, s[12:13]
	s_add_i32 s7, s5, 0x800
	s_mov_b32 m0, s7
	s_nop 0
	global_load_lds_dwordx4 v[70:71], off
	s_mov_b64 s[14:15], 0xc000
	v_lshl_add_u64 v[66:67], v[66:67], 0, s[14:15]
	s_add_i32 s7, s5, 0xc00
	s_mov_b32 m0, s7
	s_nop 0
	global_load_lds_dwordx4 v[66:67], off
	s_mov_b32 m0, s6
	s_nop 0
	global_load_lds_dwordx4 v[68:69], off
	v_lshl_add_u64 v[66:67], v[72:73], 0, s[10:11]
	s_add_i32 s6, s5, 0x4400
	s_mov_b32 m0, s6
	s_nop 0
	global_load_lds_dwordx4 v[66:67], off
	v_lshl_add_u64 v[66:67], v[68:69], 0, s[12:13]
	s_add_i32 s6, s5, 0x4800
	s_mov_b32 m0, s6
	s_nop 0
	global_load_lds_dwordx4 v[66:67], off
	v_lshl_add_u64 v[66:67], v[72:73], 0, s[14:15]
	s_addk_i32 s5, 0x4c00
	s_mov_b32 m0, s5
	s_nop 0
	global_load_lds_dwordx4 v[66:67], off

; DI int get_bid() { int b = blockIdx.x; asm volatile("" : "+s"(b)); return b; }
; template <int MT, class Epi>
; DI void gemm_tile(const u16* __restrict__ X, long ldx, const u16* __restrict__ W, long ldw, int K, char* smem,
;                   int m0, int n0, const Epi& epi, bool pre = false, const u16* Xn = nullptr, const u16* Wn = nullptr) {
;     ...
;   do {
;     asm volatile("s_waitcnt vmcnt(0)" ::: "memory");
;     __syncthreads();
;     if (kt + 1 < nk) GT_DMA((unsigned)((kt + 1) & 1) * 32768u)
;     else if (Xn != nullptr) { xe = Xn + oxe; xo = Xn + oxo; we = Wn + owe; wo = Wn + owo; GT_DMA(0u) }
;     const char* cur = smem + (kt & 1) * 32768;
; #pragma unroll
;     for (int ks = 0; ks < 2; ++ks) {
;       bf16x8 xf[MT], wf[4];
;       const int ch = ((ks * 4 + g) ^ rsw) << 4;
; #pragma unroll
;       for (int i = 0; i < MT; ++i) xf[i] = *(const bf16x8*)(cur + (wm * 16 * MT + i * 16 + lr) * 128 + ch);
; #pragma unroll
;       for (int i = 0; i < 4; ++i) wf[i] = *(const bf16x8*)(cur + 16384 + (wn * 64 + i * 16 + lr) * 128 + ch);
; #pragma unroll
;       for (int nt = 0; nt < 4; ++nt)
; #pragma unroll
;         for (int mt = 0; mt < MT; ++mt)
;           acc[nt][mt] = __builtin_amdgcn_mfma_f32_16x16x32_bf16(wf[nt], xf[mt], acc[nt][mt], 0, 0, 0);
;     }
;   } while (++kt < nk);
; DI void phase_odd(const Params& p, int o, int sub, char* smem) {
;     ...
;     for (int t = get_bid(); t < 132 * 14; t += gridDim.x) {
;       const int tm = t / 14, tn = t % 14;
;       const int t2 = t + gridDim.x, tm2 = t2 / 14, tn2 = t2 % 14;
;       const bool nx = t2 < 132 * 14;
;       gemm_tile<4>(hbuf + (size_t)tm * 128 * 1024, 1024, W + WO_IN + (size_t)tn * 128 * 1024, 1024, 1024, smem, tm * 128, tn * 128, epi, pre,
;                    nx ? hbuf + (size_t)tm2 * 128 * 1024 : nullptr, W + WO_IN + (size_t)tn2 * 128 * 1024);
;       pre = nx;
.LBB0_1026:
	s_add_i32 s7, s8, 0x8000
	v_lshl_add_u64 v[124:125], v[74:75], 0, s[40:41]
	s_and_b32 s9, s7, 0x8000
	v_lshl_add_u64 v[122:123], v[72:73], 0, s[40:41]
	v_lshl_add_u64 v[126:127], v[124:125], 0, s[74:75]
	s_and_b32 s8, s8, 0x8000
	v_or_b32_e32 v162, s8, v84
	v_add3_u32 v163, v162, v80, v81
	v_add3_u32 v164, v162, v83, v81
	v_or_b32_e32 v165, s8, v82
	v_add3_u32 v166, v165, v80, v81
	v_add3_u32 v167, v165, v83, v81
	s_waitcnt vmcnt(0)
	s_waitcnt lgkmcnt(0)
	s_barrier
	ds_read_b128 v[86:89], v163
	ds_read_b128 v[90:93], v163 offset:2048
	ds_read_b128 v[94:97], v163 offset:4096
	ds_read_b128 v[98:101], v163 offset:6144
	ds_read_b128 v[102:105], v164 offset:16384
	ds_read_b128 v[106:109], v164 offset:18432
	ds_read_b128 v[110:113], v164 offset:20480
	ds_read_b128 v[114:117], v164 offset:22528
	ds_read_b128 v[130:133], v166
	ds_read_b128 v[134:137], v166 offset:2048
	ds_read_b128 v[138:141], v166 offset:4096
	ds_read_b128 v[142:145], v166 offset:6144
	ds_read_b128 v[146:149], v167 offset:16384
	ds_read_b128 v[150:153], v167 offset:18432
	ds_read_b128 v[154:157], v167 offset:20480
	ds_read_b128 v[158:161], v167 offset:22528
	s_add_i32 s10, s9, s5
	s_mov_b32 m0, s10
	s_nop 0
	global_load_lds_dwordx4 v[126:127], off
	v_lshl_add_u64 v[126:127], v[122:123], 0, s[94:95]
	s_add_i32 s11, s10, 0x400
	s_mov_b32 m0, s11
	s_nop 0
	global_load_lds_dwordx4 v[126:127], off
	v_lshl_add_u64 v[124:125], v[124:125], 0, s[76:77]
	s_add_i32 s11, s10, 0x800
	s_mov_b32 m0, s11
	s_nop 0
	global_load_lds_dwordx4 v[124:125], off
	v_lshl_add_u64 v[120:121], v[70:71], 0, s[40:41]
	v_lshl_add_u64 v[122:123], v[122:123], 0, s[54:55]
	s_addk_i32 s10, 0xc00
	s_mov_b32 m0, s10
	s_nop 0
	global_load_lds_dwordx4 v[122:123], off
	v_lshl_add_u64 v[118:119], v[68:69], 0, s[40:41]
	v_lshl_add_u64 v[128:129], v[120:121], 0, s[28:29]
	s_add_i32 s9, s9, s6
	s_mov_b32 m0, s9
	s_nop 0
	global_load_lds_dwordx4 v[128:129], off
	v_lshl_add_u64 v[122:123], v[118:119], 0, s[94:95]
	s_add_i32 s10, s9, 0x400
	s_mov_b32 m0, s10
	s_nop 0
	global_load_lds_dwordx4 v[122:123], off
	v_lshl_add_u64 v[120:121], v[120:121], 0, s[78:79]
	s_add_i32 s10, s9, 0x800
	s_mov_b32 m0, s10
	s_nop 0
	global_load_lds_dwordx4 v[120:121], off
	v_lshl_add_u64 v[118:119], v[118:119], 0, s[54:55]
	s_addk_i32 s9, 0xc00
	s_mov_b32 m0, s9
	s_nop 0
	global_load_lds_dwordx4 v[118:119], off
	s_mov_b32 s8, s7
	s_add_u32 s40, s40, 0x80
	s_addc_u32 s41, s41, 0
	s_cmpk_lg_i32 s40, 0x780
	s_waitcnt lgkmcnt(11)
	v_mfma_f32_16x16x32_bf16 v[48:51], v[102:105], v[98:101], v[48:51]
	s_waitcnt lgkmcnt(10)
	v_mfma_f32_16x16x32_bf16 v[32:35], v[106:109], v[98:101], v[32:35]
	s_waitcnt lgkmcnt(9)
	v_mfma_f32_16x16x32_bf16 v[16:19], v[110:113], v[98:101], v[16:19]
	s_waitcnt lgkmcnt(8)
	v_mfma_f32_16x16x32_bf16 v[0:3], v[114:117], v[98:101], v[0:3]
	v_mfma_f32_16x16x32_bf16 v[60:63], v[102:105], v[86:89], v[60:63]
	v_mfma_f32_16x16x32_bf16 v[56:59], v[102:105], v[90:93], v[56:59]
	v_mfma_f32_16x16x32_bf16 v[52:55], v[102:105], v[94:97], v[52:55]
	v_mfma_f32_16x16x32_bf16 v[44:47], v[106:109], v[86:89], v[44:47]
	v_mfma_f32_16x16x32_bf16 v[40:43], v[106:109], v[90:93], v[40:43]
	v_mfma_f32_16x16x32_bf16 v[36:39], v[106:109], v[94:97], v[36:39]
	v_mfma_f32_16x16x32_bf16 v[28:31], v[110:113], v[86:89], v[28:31]
	v_mfma_f32_16x16x32_bf16 v[24:27], v[110:113], v[90:93], v[24:27]
	v_mfma_f32_16x16x32_bf16 v[20:23], v[110:113], v[94:97], v[20:23]
	v_mfma_f32_16x16x32_bf16 v[12:15], v[114:117], v[86:89], v[12:15]
	v_mfma_f32_16x16x32_bf16 v[8:11], v[114:117], v[90:93], v[8:11]
	v_mfma_f32_16x16x32_bf16 v[4:7], v[114:117], v[94:97], v[4:7]
	s_waitcnt lgkmcnt(3)
	v_mfma_f32_16x16x32_bf16 v[60:63], v[146:149], v[130:133], v[60:63]
	v_mfma_f32_16x16x32_bf16 v[56:59], v[146:149], v[134:137], v[56:59]
	v_mfma_f32_16x16x32_bf16 v[52:55], v[146:149], v[138:141], v[52:55]
	v_mfma_f32_16x16x32_bf16 v[48:51], v[146:149], v[142:145], v[48:51]
	s_waitcnt lgkmcnt(2)
	v_mfma_f32_16x16x32_bf16 v[44:47], v[150:153], v[130:133], v[44:47]
	v_mfma_f32_16x16x32_bf16 v[40:43], v[150:153], v[134:137], v[40:43]
	v_mfma_f32_16x16x32_bf16 v[36:39], v[150:153], v[138:141], v[36:39]
	v_mfma_f32_16x16x32_bf16 v[32:35], v[150:153], v[142:145], v[32:35]
	s_waitcnt lgkmcnt(1)
	v_mfma_f32_16x16x32_bf16 v[28:31], v[154:157], v[130:133], v[28:31]
	v_mfma_f32_16x16x32_bf16 v[24:27], v[154:157], v[134:137], v[24:27]
	v_mfma_f32_16x16x32_bf16 v[20:23], v[154:157], v[138:141], v[20:23]
	v_mfma_f32_16x16x32_bf16 v[16:19], v[154:157], v[142:145], v[16:19]
	s_waitcnt lgkmcnt(0)
	v_mfma_f32_16x16x32_bf16 v[12:15], v[158:161], v[130:133], v[12:15]
	v_mfma_f32_16x16x32_bf16 v[8:11], v[158:161], v[134:137], v[8:11]
	v_mfma_f32_16x16x32_bf16 v[4:7], v[158:161], v[138:141], v[4:7]
	v_mfma_f32_16x16x32_bf16 v[0:3], v[158:161], v[142:145], v[0:3]
	s_cbranch_scc1 .LBB0_1026
	v_readlane_b32 s8, v255, 5
	v_readlane_b32 s14, v255, 11
	s_add_i32 s4, s4, s14
	s_mul_hi_i32 s7, s4, 0x92492493
	s_add_i32 s7, s7, s4
	s_lshr_b32 s8, s7, 31
	s_ashr_i32 s7, s7, 3
	s_add_i32 s46, s7, s8
	s_cmpk_gt_i32 s4, 0x737
	v_readlane_b32 s9, v255, 6
	s_cselect_b64 s[40:41], -1, 0
	s_ashr_i32 s47, s46, 31
	s_lshl_b64 s[8:9], s[46:47], 18
	s_add_u32 s7, s0, s8
	s_addc_u32 s8, s1, s9
	s_cmpk_lt_i32 s4, 0x738
	s_waitcnt vmcnt(0)
	s_cselect_b32 s45, s8, 0
	s_cselect_b32 s44, s7, 0
	v_readlane_b32 s12, v255, 9
	v_readlane_b32 s13, v255, 10
	s_cmp_eq_u64 s[44:45], 0
	v_readlane_b32 s10, v255, 7
	v_readlane_b32 s11, v255, 8
	v_readlane_b32 s15, v255, 12
	s_barrier
	s_cbranch_scc1 .LBB0_1029
	s_mul_i32 s7, s46, 14
	s_sub_i32 s8, s4, s7
	s_ashr_i32 s9, s8, 31
	s_lshl_b64 s[8:9], s[8:9], 18
	s_add_u32 s8, s12, s8
	s_addc_u32 s9, s13, s9
	v_lshl_add_u64 v[68:69], s[44:45], 0, v[66:67]
	v_lshl_add_u64 v[70:71], s[8:9], 0, v[64:65]
	v_lshl_add_u64 v[64:65], s[44:45], 0, v[64:65]
	s_mov_b32 m0, s5
	s_nop 0
	global_load_lds_dwordx4 v[68:69], off
	s_mov_b64 s[10:11], 0x4000
	v_lshl_add_u64 v[66:67], s[8:9], 0, v[66:67]
	v_lshl_add_u64 v[72:73], v[64:65], 0, s[10:11]
	s_add_i32 s7, s5, 0x400
	s_mov_b32 m0, s7
	s_nop 0
	global_load_lds_dwordx4 v[72:73], off
	s_mov_b64 s[12:13], 0x8000
	v_lshl_add_u64 v[68:69], v[68:69], 0, s[12:13]
	s_add_i32 s7, s5, 0x800
	s_mov_b32 m0, s7
	s_nop 0
	global_load_lds_dwordx4 v[68:69], off
	s_mov_b64 s[14:15], 0xc000
	v_lshl_add_u64 v[64:65], v[64:65], 0, s[14:15]
	s_add_i32 s7, s5, 0xc00
	s_mov_b32 m0, s7
	s_nop 0
	global_load_lds_dwordx4 v[64:65], off
	s_mov_b32 m0, s6
	s_nop 0
	global_load_lds_dwordx4 v[66:67], off
	v_lshl_add_u64 v[64:65], v[70:71], 0, s[10:11]
	s_add_i32 s6, s5, 0x4400
	s_mov_b32 m0, s6
	s_nop 0
	global_load_lds_dwordx4 v[64:65], off
	v_lshl_add_u64 v[64:65], v[66:67], 0, s[12:13]
	s_add_i32 s6, s5, 0x4800
	s_mov_b32 m0, s6
	s_nop 0
	global_load_lds_dwordx4 v[64:65], off
	v_lshl_add_u64 v[64:65], v[70:71], 0, s[14:15]
	s_addk_i32 s5, 0x4c00
	s_mov_b32 m0, s5
	s_nop 0
	global_load_lds_dwordx4 v[64:65], off

; template <int MT, class Epi>
; DI void gemm_tile(const u16* __restrict__ X, long ldx, const u16* __restrict__ W, long ldw, int K, char* smem,
;                   int m0, int n0, const Epi& epi, bool pre = false, const u16* Xn = nullptr, const u16* Wn = nullptr) {
;     ...
;   do {
;     asm volatile("s_waitcnt vmcnt(0)" ::: "memory");
;     __syncthreads();
;     if (kt + 1 < nk) GT_DMA((unsigned)((kt + 1) & 1) * 32768u)
;     else if (Xn != nullptr) { xe = Xn + oxe; xo = Xn + oxo; we = Wn + owe; wo = Wn + owo; GT_DMA(0u) }
;     const char* cur = smem + (kt & 1) * 32768;
; #pragma unroll
;     for (int ks = 0; ks < 2; ++ks) {
;       bf16x8 xf[MT], wf[4];
;       const int ch = ((ks * 4 + g) ^ rsw) << 4;
; #pragma unroll
;       for (int i = 0; i < MT; ++i) xf[i] = *(const bf16x8*)(cur + (wm * 16 * MT + i * 16 + lr) * 128 + ch);
; #pragma unroll
;       for (int i = 0; i < 4; ++i) wf[i] = *(const bf16x8*)(cur + 16384 + (wn * 64 + i * 16 + lr) * 128 + ch);
; #pragma unroll
;       for (int nt = 0; nt < 4; ++nt)
; #pragma unroll
;         for (int mt = 0; mt < MT; ++mt)
;           acc[nt][mt] = __builtin_amdgcn_mfma_f32_16x16x32_bf16(wf[nt], xf[mt], acc[nt][mt], 0, 0, 0);
;     }
;   } while (++kt < nk);
.LBB0_1312:
	s_add_i32 s7, s8, 0x8000
	v_lshl_add_u64 v[124:125], v[74:75], 0, s[40:41]
	s_and_b32 s9, s7, 0x8000
	v_lshl_add_u64 v[122:123], v[72:73], 0, s[40:41]
	v_lshl_add_u64 v[126:127], v[124:125], 0, s[74:75]
	s_and_b32 s8, s8, 0x8000
	v_or_b32_e32 v162, s8, v84
	v_add3_u32 v163, v162, v80, v81
	v_add3_u32 v164, v162, v83, v81
	v_or_b32_e32 v165, s8, v82
	v_add3_u32 v166, v165, v80, v81
	v_add3_u32 v167, v165, v83, v81
	s_waitcnt vmcnt(0)
	s_waitcnt lgkmcnt(0)
	s_barrier
	ds_read_b128 v[86:89], v163
	ds_read_b128 v[90:93], v163 offset:2048
	ds_read_b128 v[94:97], v163 offset:4096
	ds_read_b128 v[98:101], v163 offset:6144
	ds_read_b128 v[102:105], v164 offset:16384
	ds_read_b128 v[106:109], v164 offset:18432
	ds_read_b128 v[110:113], v164 offset:20480
	ds_read_b128 v[114:117], v164 offset:22528
	ds_read_b128 v[130:133], v166
	ds_read_b128 v[134:137], v166 offset:2048
	ds_read_b128 v[138:141], v166 offset:4096
	ds_read_b128 v[142:145], v166 offset:6144
	ds_read_b128 v[146:149], v167 offset:16384
	ds_read_b128 v[150:153], v167 offset:18432
	ds_read_b128 v[154:157], v167 offset:20480
	ds_read_b128 v[158:161], v167 offset:22528
	s_add_i32 s10, s9, s5
	s_mov_b32 m0, s10
	s_nop 0
	global_load_lds_dwordx4 v[126:127], off
	v_lshl_add_u64 v[126:127], v[122:123], 0, s[94:95]
	s_add_i32 s11, s10, 0x400
	s_mov_b32 m0, s11
	s_nop 0
	global_load_lds_dwordx4 v[126:127], off
	v_lshl_add_u64 v[124:125], v[124:125], 0, s[76:77]
	s_add_i32 s11, s10, 0x800
	s_mov_b32 m0, s11
	s_nop 0
	global_load_lds_dwordx4 v[124:125], off
	v_lshl_add_u64 v[120:121], v[70:71], 0, s[40:41]
	v_lshl_add_u64 v[122:123], v[122:123], 0, s[54:55]
	s_addk_i32 s10, 0xc00
	s_mov_b32 m0, s10
	s_nop 0
	global_load_lds_dwordx4 v[122:123], off
	v_lshl_add_u64 v[118:119], v[68:69], 0, s[40:41]
	v_lshl_add_u64 v[128:129], v[120:121], 0, s[28:29]
	s_add_i32 s9, s9, s6
	s_mov_b32 m0, s9
	s_nop 0
	global_load_lds_dwordx4 v[128:129], off
	v_lshl_add_u64 v[122:123], v[118:119], 0, s[94:95]
	s_add_i32 s10, s9, 0x400
	s_mov_b32 m0, s10
	s_nop 0
	global_load_lds_dwordx4 v[122:123], off
	v_lshl_add_u64 v[120:121], v[120:121], 0, s[78:79]
	s_add_i32 s10, s9, 0x800
	s_mov_b32 m0, s10
	s_nop 0
	global_load_lds_dwordx4 v[120:121], off
	v_lshl_add_u64 v[118:119], v[118:119], 0, s[54:55]
	s_addk_i32 s9, 0xc00
	s_mov_b32 m0, s9
	s_nop 0
	global_load_lds_dwordx4 v[118:119], off
	s_mov_b32 s8, s7
	s_add_u32 s40, s40, 0x80
	s_addc_u32 s41, s41, 0
	s_cmpk_lg_i32 s40, 0x780
	s_waitcnt lgkmcnt(11)
	v_mfma_f32_16x16x32_bf16 v[48:51], v[102:105], v[98:101], v[48:51]
	s_waitcnt lgkmcnt(10)
	v_mfma_f32_16x16x32_bf16 v[32:35], v[106:109], v[98:101], v[32:35]
	s_waitcnt lgkmcnt(9)
	v_mfma_f32_16x16x32_bf16 v[16:19], v[110:113], v[98:101], v[16:19]
	s_waitcnt lgkmcnt(8)
	v_mfma_f32_16x16x32_bf16 v[0:3], v[114:117], v[98:101], v[0:3]
	v_mfma_f32_16x16x32_bf16 v[60:63], v[102:105], v[86:89], v[60:63]
	v_mfma_f32_16x16x32_bf16 v[56:59], v[102:105], v[90:93], v[56:59]
	v_mfma_f32_16x16x32_bf16 v[52:55], v[102:105], v[94:97], v[52:55]
	v_mfma_f32_16x16x32_bf16 v[44:47], v[106:109], v[86:89], v[44:47]
	v_mfma_f32_16x16x32_bf16 v[40:43], v[106:109], v[90:93], v[40:43]
	v_mfma_f32_16x16x32_bf16 v[36:39], v[106:109], v[94:97], v[36:39]
	v_mfma_f32_16x16x32_bf16 v[28:31], v[110:113], v[86:89], v[28:31]
	v_mfma_f32_16x16x32_bf16 v[24:27], v[110:113], v[90:93], v[24:27]
	v_mfma_f32_16x16x32_bf16 v[20:23], v[110:113], v[94:97], v[20:23]
	v_mfma_f32_16x16x32_bf16 v[12:15], v[114:117], v[86:89], v[12:15]
	v_mfma_f32_16x16x32_bf16 v[8:11], v[114:117], v[90:93], v[8:11]
	v_mfma_f32_16x16x32_bf16 v[4:7], v[114:117], v[94:97], v[4:7]
	s_waitcnt lgkmcnt(3)
	v_mfma_f32_16x16x32_bf16 v[60:63], v[146:149], v[130:133], v[60:63]
	v_mfma_f32_16x16x32_bf16 v[56:59], v[146:149], v[134:137], v[56:59]
	v_mfma_f32_16x16x32_bf16 v[52:55], v[146:149], v[138:141], v[52:55]
	v_mfma_f32_16x16x32_bf16 v[48:51], v[146:149], v[142:145], v[48:51]
	s_waitcnt lgkmcnt(2)
	v_mfma_f32_16x16x32_bf16 v[44:47], v[150:153], v[130:133], v[44:47]
	v_mfma_f32_16x16x32_bf16 v[40:43], v[150:153], v[134:137], v[40:43]
	v_mfma_f32_16x16x32_bf16 v[36:39], v[150:153], v[138:141], v[36:39]
	v_mfma_f32_16x16x32_bf16 v[32:35], v[150:153], v[142:145], v[32:35]
	s_waitcnt lgkmcnt(1)
	v_mfma_f32_16x16x32_bf16 v[28:31], v[154:157], v[130:133], v[28:31]
	v_mfma_f32_16x16x32_bf16 v[24:27], v[154:157], v[134:137], v[24:27]
	v_mfma_f32_16x16x32_bf16 v[20:23], v[154:157], v[138:141], v[20:23]
	v_mfma_f32_16x16x32_bf16 v[16:19], v[154:157], v[142:145], v[16:19]
	s_waitcnt lgkmcnt(0)
	v_mfma_f32_16x16x32_bf16 v[12:15], v[158:161], v[130:133], v[12:15]
	v_mfma_f32_16x16x32_bf16 v[8:11], v[158:161], v[134:137], v[8:11]
	v_mfma_f32_16x16x32_bf16 v[4:7], v[158:161], v[138:141], v[4:7]
	v_mfma_f32_16x16x32_bf16 v[0:3], v[158:161], v[142:145], v[0:3]
	s_cbranch_scc1 .LBB0_1312
; DI int get_bid() { int b = blockIdx.x; asm volatile("" : "+s"(b)); return b; }
; DI float gelu_f(float x) { return 0.5f * x * (1.f + erff(x * 0.70710678118654752f)); }
; DI float silu_f(float x) { return x * __builtin_amdgcn_rcpf(1.f + __expf(-x)); }
; DI void phase_even(const Params& p, int e, int sub, char* smem) {
;     ...
;     for (int t = get_bid(); t < 132 * 40; t += gridDim.x) {
;       const int tm = t / 40, tn = t % 40;
;       const int t2 = t + gridDim.x, tm2 = t2 / 40, tn2 = t2 % 40;
;       const bool nx = t2 < 132 * 40;
;       gemm_tile<4>(hbuf + (size_t)tm * 128 * 1024, 1024, W + WE_IN + (size_t)tn * 128 * 1024, 1024, 1024, smem, tm * 128, tn * 128, epi, pre,
;                    nx ? hbuf + (size_t)tm2 * 128 * 1024 : nullptr, W + WE_IN + (size_t)tn2 * 128 * 1024);
;       pre = nx;
;     }
	v_mov_b32_e32 v170, 0x3f3504f3
	v_mov_b32_e32 v171, 0x3f3504f3
	v_mov_b32_e32 v172, 0xbfb8aa3b
	v_mov_b32_e32 v173, 0xbfb8aa3b
	v_mov_b32_e32 v174, 0x378e98ab
	v_mov_b32_e32 v175, 0x378e98ab
	v_mov_b32_e32 v176, 0xb9c68948
	v_mov_b32_e32 v177, 0xb9c68948
	v_mov_b32_e32 v178, 0x3b7cd369
	v_mov_b32_e32 v179, 0x3b7cd369
	v_mov_b32_e32 v180, 0xbcc618b2
	v_mov_b32_e32 v181, 0xbcc618b2
	v_mov_b32_e32 v186, 0x3dda74e4
	v_mov_b32_e32 v187, 0x3dda74e4
	v_mov_b32_e32 v188, 0x3f228afd
	v_mov_b32_e32 v189, 0x3f228afd
	v_mov_b32_e32 v190, 0x3e03c728
	v_mov_b32_e32 v191, 0x3e03c728
	v_mov_b32_e32 v192, 0xba1345e1
	v_mov_b32_e32 v193, 0xba1345e1
	v_mov_b32_e32 v194, 0x3ba10414
	v_mov_b32_e32 v195, 0x3ba10414
	v_mov_b32_e32 v196, 0xbcdac9b8
	v_mov_b32_e32 v197, 0xbcdac9b8
	v_mov_b32_e32 v224, 0x3de703be
	v_mov_b32_e32 v225, 0x3de703be
	v_mov_b32_e32 v226, 0xbec09330
	v_mov_b32_e32 v227, 0xbec09330
	v_mov_b32_e32 v228, 0x3e0375d0
	v_mov_b32_e32 v229, 0x3e0375d0
	v_mov_b32_e32 v230, 1.0
	v_mov_b32_e32 v231, 1.0
	v_mov_b32_e32 v232, 0.5
	v_mov_b32_e32 v233, 0.5
	v_mov_b32_e32 v234, -1.0
	v_mov_b32_e32 v235, -1.0
	v_readlane_b32 s8, v255, 5
	v_readlane_b32 s14, v255, 11
	s_add_i32 s4, s4, s14
	s_mul_hi_i32 s7, s4, 0x66666667
	s_lshr_b32 s8, s7, 31
	s_ashr_i32 s7, s7, 4
	s_add_i32 s46, s7, s8
	s_cmpk_gt_i32 s4, 0x149f
	v_readlane_b32 s9, v255, 6
	s_cselect_b64 s[44:45], -1, 0
	s_ashr_i32 s47, s46, 31
	s_lshl_b64 s[8:9], s[46:47], 18
	s_add_u32 s7, s0, s8
	s_addc_u32 s8, s1, s9
	s_cmpk_lt_i32 s4, 0x14a0
	s_waitcnt vmcnt(0)
	s_cselect_b32 s41, s8, 0
	s_cselect_b32 s40, s7, 0
	v_readlane_b32 s12, v255, 9
	v_readlane_b32 s13, v255, 10
	s_cmp_eq_u64 s[40:41], 0
	v_readlane_b32 s10, v255, 7
	v_readlane_b32 s11, v255, 8
	v_readlane_b32 s15, v255, 12
	s_barrier
	s_cbranch_scc1 .LBB0_1315
	s_mul_i32 s7, s46, 40
	s_sub_i32 s8, s4, s7
	s_ashr_i32 s9, s8, 31
	s_lshl_b64 s[8:9], s[8:9], 18
	s_add_u32 s8, s12, s8
	s_addc_u32 s9, s13, s9
	v_lshl_add_u64 v[68:69], s[40:41], 0, v[66:67]
	v_lshl_add_u64 v[70:71], s[8:9], 0, v[64:65]
	v_lshl_add_u64 v[64:65], s[40:41], 0, v[64:65]
	s_mov_b32 m0, s5
	s_nop 0
	global_load_lds_dwordx4 v[68:69], off
	s_mov_b64 s[10:11], 0x4000
	v_lshl_add_u64 v[66:67], s[8:9], 0, v[66:67]
	v_lshl_add_u64 v[72:73], v[64:65], 0, s[10:11]
	s_add_i32 s7, s5, 0x400
	s_mov_b32 m0, s7
	s_nop 0
	global_load_lds_dwordx4 v[72:73], off
	s_mov_b64 s[12:13], 0x8000
	v_lshl_add_u64 v[68:69], v[68:69], 0, s[12:13]
	s_add_i32 s7, s5, 0x800
	s_mov_b32 m0, s7
	s_nop 0
	global_load_lds_dwordx4 v[68:69], off
	s_mov_b64 s[14:15], 0xc000
	v_lshl_add_u64 v[64:65], v[64:65], 0, s[14:15]
	s_add_i32 s7, s5, 0xc00
	s_mov_b32 m0, s7
	s_nop 0
	global_load_lds_dwordx4 v[64:65], off
	s_mov_b32 m0, s6
	s_nop 0
	global_load_lds_dwordx4 v[66:67], off
	v_lshl_add_u64 v[64:65], v[70:71], 0, s[10:11]
	s_add_i32 s6, s5, 0x4400
	s_mov_b32 m0, s6
	s_nop 0
	global_load_lds_dwordx4 v[64:65], off
	v_lshl_add_u64 v[64:65], v[66:67], 0, s[12:13]
	s_add_i32 s6, s5, 0x4800
	s_mov_b32 m0, s6
	s_nop 0
	global_load_lds_dwordx4 v[64:65], off
	v_lshl_add_u64 v[64:65], v[70:71], 0, s[14:15]
	s_addk_i32 s5, 0x4c00
	s_mov_b32 m0, s5
	s_nop 0
	global_load_lds_dwordx4 v[64:65], off
